# GDN scan with loader waves: waves 1-3 of a scan workgroup stream the LDS ring (LDS-DMA) with LDS flag hand-off, wave 0 only reads LDS / computes / stores
# baseline (speedup 1.0000x reference)
; #define LAS __attribute__((address_space(3)))
; __device__ __forceinline__ unsigned xb_add(unsigned* p, unsigned v) { return __hip_atomic_fetch_add(p, v, __ATOMIC_RELAXED, __HIP_MEMORY_SCOPE_AGENT); }
; __device__ __forceinline__ unsigned xb_xcc_id() { return (unsigned)__builtin_amdgcn_s_getreg((3 << 11) | 20) & 0xFu; }
; __device__ __forceinline__ XcdBarrier xcd_barrier_post(unsigned* bar, volatile LAS unsigned* st) {
;     XcdBarrier b; b.bar = bar; b.x = xb_xcc_id(); b.st = st;
;     if (threadIdx.x == 0) (void)xb_add(&bar[XB_XCNT(b.x)], 1u);
;     return b;
; __global__ void __launch_bounds__(512, 2) fwd_kernel(Args args) {
;     ...
;     c.out = args.out; c.ws = args.ws;
;     c.tid = threadIdx.x; c.lane = c.tid & 63; c.wave = __builtin_amdgcn_readfirstlane(c.tid >> 6); c.G = gridDim.x; c.bid = blockIdx.x;
;     c.layer = 0; c.slab = 0; c.nseq = 8; c.seqlen = 4096; c.stok = 32768; c.sbase = 0; c.dry = 0;
;     const int lo = args.ph_lo, hi = args.ph_hi;
;     volatile LAS unsigned* MISC = (volatile LAS unsigned*)(L + LDS_MISC);
;     if (c.tid < 4) MISC[c.tid] = 0u;
;     __syncthreads();
;     XcdBarrier bar; bar.bar = (unsigned*)(c.ws + WS_CTL) + 1024; bar.x = 0; bar.st = MISC;
;     if (hi - lo > 1) bar = xcd_barrier_post((unsigned*)(c.ws + WS_CTL) + 1024, MISC);
_Z10fwd_kernel4Args:
	s_mov_b64 s[80:81], s[0:1]
	s_load_dwordx4 s[84:87], s[0:1], 0xa8
	s_load_dword s79, s[0:1], 0xb8
	s_add_u32 s0, s80, 0xb8
	s_addc_u32 s1, s81, 0
	s_mov_b32 s78, s2
	v_writelane_b32 v253, s0, 0
	v_cmp_gt_u32_e32 vcc, 4, v0
	s_nop 0
	v_writelane_b32 v253, s1, 1
	s_and_saveexec_b64 s[0:1], vcc
	v_lshl_add_u32 v1, v0, 2, 0
	v_add_u32_e32 v1, 0x23800, v1
	v_mov_b32_e32 v2, 0
	ds_write_b32 v1, v2
	ds_write_b32 v1, v2 offset:5632
	s_or_b64 exec, exec, s[0:1]
	s_waitcnt lgkmcnt(0)
	s_add_u32 s82, s84, 0x1000
	s_addc_u32 s83, s85, 0
	s_sub_i32 s2, s87, s86
	s_mov_b64 s[0:1], 0
	s_cmp_lt_i32 s2, 2
	v_cmp_eq_u32_e32 vcc, 0, v0
	s_mov_b64 s[84:85], 0
	s_barrier
	s_cbranch_scc1 .LBB0_7
	s_getreg_b32 s2, hwreg(HW_REG_XCC_ID, 0, 4)
	s_lshl_b32 s2, s2, 6
	s_and_b32 s84, s2, 0x3c0
	s_and_saveexec_b64 s[2:3], vcc
	s_cbranch_execz .LBB0_6
	s_mov_b64 s[4:5], exec
	v_mbcnt_lo_u32_b32 v1, s4, 0
	v_mbcnt_hi_u32_b32 v1, s5, v1
	v_cmp_eq_u32_e32 vcc, 0, v1
	s_and_b64 s[6:7], exec, vcc
	s_mov_b64 exec, s[6:7]
	s_cbranch_execz .LBB0_6
	s_lshl_b32 s6, s84, 2
	s_bcnt1_i32_b64 s4, s[4:5]
	v_mov_b32_e32 v1, s6
	v_mov_b32_e32 v2, s4
	global_atomic_add v1, v2, s[82:83] offset:1024

; #define LAS __attribute__((address_space(3)))
; DI f32x16 zero16() { f32x16 z; for (int i = 0; i < 16; ++i) z[i] = 0.f; return z; }
; DI void phase_scan(KArgs args, LAS unsigned char* L, const Ctx& c) {
;     ...
;     const int nwu = c.nseq * 24, wu = c.bid;
;     if (wu < nwu && c.wave == 0) {
;         const int lane = c.lane;
;         const int chain = wu >> 1, nt = wu & 1, seq = chain / 12, rem = chain % 12, head = rem >> 1, dir = rem & 1;
;         const int nch = c.seqlen >> 6, gch0 = seq * nch;
;         unsigned char* GS = BIGP(unsigned char, B_GSCR);
;         f32x16 S[2]; S[0] = zero16(); S[1] = zero16();
;         bf16x8 A[2][2][4]; u32x4 cm[2][2][2];
;         const long gstep = (long)(dir ? -1 : 1) * 12 * GSTRIDE;
;         const unsigned char* G0 = GS + (size_t)(((gch0 + (dir ? nch - 1 : 0)) * 6 + head) * 2 + dir) * GSTRIDE;
;         unsigned char* Gs = (unsigned char*)G0;
;         float glv[4];
; #pragma unroll
;         for (int q = 0; q < 4; ++q) { const int sq = q * 64 + lane; glv[q] = *(const float*)(G0 + (long)(sq < nch ? sq : nch - 1) * gstep + 40960); }
;         LAS unsigned char* RING = L + 81920;
;         int dslot = 0, rslot = 0, dstage = 0;
;     ...
;         SCAN_DMA(); SCAN_DMA(); SCAN_DMA(); SCAN_DMA(); SCAN_DMA();
;         asm volatile("s_waitcnt vmcnt(48)" ::: "memory"); SCAN_LOAD(0);
;         asm volatile("s_waitcnt vmcnt(36)" ::: "memory"); SCAN_LOAD(1);
;         for (int step = 0; step < nch; step += 2) {
.LBB0_646:
	s_movk_i32 s33, 0x600
	s_and_b64 vcc, exec, s[0:1]
	s_cbranch_vccz .LBB0_946
	v_readlane_b32 s2, v254, 23
	s_lshr_b32 s30, s60, 6
	v_readlane_b32 s3, v254, 24
	s_and_b64 s[0:1], s[2:3], exec
	s_cselect_b32 s0, 6, 8
	s_add_i32 s31, s30, -1
	v_writelane_b32 v254, s0, 32
	s_and_b64 s[0:1], s[2:3], exec
	s_cselect_b32 s2, 0xc0, 24
	s_cmpk_lt_u32 s61, 0x100
	s_cselect_b64 s[0:1], -1, 0
	s_cmp_lt_i32 s68, s2
	s_cselect_b64 s[2:3], -1, 0
	s_and_b64 s[0:1], s[2:3], s[0:1]
	s_andn2_b64 vcc, exec, s[0:1]
	s_movk_i32 s27, 0x90
	v_readlane_b32 s28, v254, 27
	v_readlane_b32 s29, v254, 29
	s_cbranch_vccnz .LBB0_651
	s_setprio 3
	s_ashr_i32 s0, s68, 1
	s_mul_hi_i32 s1, s0, 0x2aaaaaab
	s_lshr_b32 s2, s1, 31
	s_ashr_i32 s1, s1, 1
	s_add_i32 s1, s1, s2
	s_mul_i32 s2, s1, 12
	s_sub_i32 s2, s0, s2
	v_readlane_b32 s4, v254, 32
	s_bfe_i32 s3, s2, 0x10000
	s_and_b32 s0, s2, 1
	s_lshl_b32 s4, s1, s4
	s_cmp_eq_u32 s0, 0
	s_mov_b32 s0, 0x78c00
	s_cselect_b32 s1, 0, -1
	s_cselect_b32 s0, s0, 0xfff87400
	s_and_b32 s3, s3, s31
	s_add_i32 s3, s3, s4
	s_mul_i32 s3, s3, 12
	s_add_i32 s24, s3, s2
	s_mul_hi_i32 s23, s24, 0xa100
	s_mul_i32 s24, s24, 0xa100
	s_waitcnt lgkmcnt(0)
	s_add_u32 s6, s72, s24
	s_addc_u32 s7, s73, s23
	s_add_u32 s2, s6, 0x37800000
	s_addc_u32 s3, s7, 0
	v_min_i32_e32 v1, s31, v28
	v_mov_b64_e32 v[4:5], s[2:3]
	v_mad_u64_u32 v[6:7], s[4:5], s0, v1, v[4:5]
	v_mad_i32_i24 v1, s1, v1, v7
	v_or_b32_e32 v7, 64, v28
	v_min_i32_e32 v2, s31, v7
	v_mad_u64_u32 v[8:9], s[4:5], s0, v2, v[4:5]
	v_or_b32_e32 v12, 0x80, v28
	v_mad_i32_i24 v9, s1, v2, v9
	v_min_i32_e32 v2, s31, v12
	v_mad_u64_u32 v[10:11], s[4:5], s0, v2, v[4:5]
	v_or_b32_e32 v13, 0xc0, v28
	v_mad_i32_i24 v11, s1, v2, v11
	v_min_i32_e32 v2, s31, v13
	v_mad_u64_u32 v[4:5], s[4:5], s0, v2, v[4:5]
	s_add_u32 s20, s6, 0x37802000
	s_addc_u32 s21, s7, 0
	s_lshl_b32 s4, s68, 12
	s_and_b32 s25, s4, 0x1000
	s_add_u32 s18, s2, s0
	s_addc_u32 s19, s3, s1
	s_add_u32 s16, s18, 0x2000
	s_addc_u32 s17, s19, 0
	s_add_u32 s14, s18, s0
	s_addc_u32 s15, s19, s1
	s_add_u32 s12, s14, 0x2000
	s_addc_u32 s13, s15, 0
	s_add_u32 s10, s14, s0
	s_addc_u32 s11, s15, s1
	s_mov_b32 s26, 0xa000
	s_add_u32 s8, s10, 0x2000
	v_add_co_u32_e32 v6, vcc, s26, v6
	v_lshlrev_b32_e32 v148, 4, v7
	s_addc_u32 s9, s11, 0
	v_addc_co_u32_e32 v7, vcc, 0, v1, vcc
	s_add_u32 s6, s10, s0
	v_add_co_u32_e32 v8, vcc, s26, v8
	s_addc_u32 s7, s11, s1
	s_nop 0
	v_addc_co_u32_e32 v9, vcc, 0, v9, vcc
	s_add_u32 s4, s6, 0x2000
	v_add_co_u32_e32 v10, vcc, s26, v10
	s_addc_u32 s5, s7, 0
	s_add_i32 s22, 0, 0x14000
	v_addc_co_u32_e32 v11, vcc, 0, v11, vcc
	v_mad_i32_i24 v5, s1, v2, v5
	v_lshlrev_b32_e32 v2, 4, v28
	v_add_co_u32_e32 v4, vcc, s26, v4
	v_addc_co_u32_e32 v5, vcc, 0, v5, vcc
	global_load_dword v1, v[6:7], off
	global_load_dword v168, v[8:9], off
	global_load_dword v169, v[10:11], off
	global_load_dword v170, v[4:5], off
	v_lshlrev_b32_e32 v150, 4, v12
	v_lshlrev_b32_e32 v152, 4, v13
	v_or_b32_e32 v154, 0x1000, v2
	v_or_b32_e32 v156, 0x1400, v2
	v_or_b32_e32 v158, 0x1800, v2
	v_or_b32_e32 v160, 0x1c00, v2
	v_lshl_or_b32 v162, v28, 5, s25
	v_mov_b32_e32 v163, v3
	v_lshl_add_u64 v[12:13], s[20:21], 0, v[162:163]
	v_lshl_add_u64 v[12:13], v[12:13], 0, 16
	v_or_b32_e32 v164, 0x800, v162
	v_mov_b32_e32 v165, v3
	v_lshl_add_u64 v[14:15], s[20:21], 0, v[164:165]
	v_lshl_add_u64 v[14:15], v[14:15], 0, 16
	v_lshl_add_u64 v[16:17], s[16:17], 0, v[162:163]
	v_lshl_add_u64 v[16:17], v[16:17], 0, 16
	v_lshl_add_u64 v[18:19], s[16:17], 0, v[164:165]
	v_lshl_add_u64 v[18:19], v[18:19], 0, 16
	v_lshl_add_u64 v[20:21], s[12:13], 0, v[162:163]
	v_lshl_add_u64 v[20:21], v[20:21], 0, 16
	v_lshl_add_u64 v[22:23], s[12:13], 0, v[164:165]
	v_lshl_add_u64 v[22:23], v[22:23], 0, 16
	v_lshl_add_u64 v[24:25], s[8:9], 0, v[162:163]
	v_lshl_add_u64 v[24:25], v[24:25], 0, 16
	v_lshl_add_u64 v[26:27], s[8:9], 0, v[164:165]
	v_lshl_add_u64 v[26:27], v[26:27], 0, 16
	v_lshl_add_u64 v[28:29], s[4:5], 0, v[162:163]
	v_lshl_add_u64 v[28:29], v[28:29], 0, 16
	v_lshl_add_u64 v[30:31], s[4:5], 0, v[164:165]
	v_lshl_add_u64 v[30:31], v[30:31], 0, 16
	s_add_u32 s4, s24, s25
	s_addc_u32 s5, s23, 0
	s_add_u32 s4, s72, s4
	s_addc_u32 s5, s73, s5
	v_lshl_add_u64 v[4:5], s[4:5], 0, v[2:3]
	s_mov_b64 s[4:5], 0x37808800
	v_lshl_add_u64 v[166:167], v[4:5], 0, s[4:5]
	v_mov_b32_e32 v4, 0
	v_mov_b32_e32 v149, v3
	v_mov_b32_e32 v151, v3
	v_mov_b32_e32 v153, v3
	v_mov_b32_e32 v155, v3
	v_mov_b32_e32 v157, v3
	v_mov_b32_e32 v159, v3
	v_mov_b32_e32 v161, v3
	s_lshl_b64 s[8:9], s[0:1], 1
	v_mov_b32_e32 v5, v4
	v_mov_b32_e32 v6, v4
	v_mov_b32_e32 v7, v4
	v_mov_b32_e32 v8, v4
	v_mov_b32_e32 v9, v4
	v_mov_b32_e32 v10, v4
	v_mov_b32_e32 v11, v4
	v_mov_b32_e32 v12, v4
	v_mov_b32_e32 v13, v4
	v_mov_b32_e32 v14, v4
	v_mov_b32_e32 v15, v4
	v_mov_b32_e32 v16, v4
	v_mov_b32_e32 v17, v4
	v_mov_b32_e32 v18, v4
	v_mov_b32_e32 v19, v4
	v_mov_b32_e32 v20, v4
	v_mov_b32_e32 v21, v4
	v_mov_b32_e32 v22, v4
	v_mov_b32_e32 v23, v4
	v_mov_b32_e32 v24, v4
	v_mov_b32_e32 v25, v4
	v_mov_b32_e32 v26, v4
	v_mov_b32_e32 v27, v4
	v_mov_b32_e32 v28, v4
	v_mov_b32_e32 v29, v4
	v_mov_b32_e32 v30, v4
	v_mov_b32_e32 v31, v4
	v_mov_b32_e32 v32, v4
	v_mov_b32_e32 v33, v4
	v_mov_b32_e32 v34, v4
	v_mov_b32_e32 v35, v4
	v_mov_b32_e32 v173, 0x24e00
	s_lshr_b32 s6, s61, 6
	s_cmp_eq_u32 s6, 0
	s_cbranch_scc1 .Lsc_consumer
	s_add_i32 s7, s6, -1
	s_lshl_b32 s20, s7, 12
	s_lshl_b32 s7, s7, 2
	v_add_u32_e32 v246, s7, v173
	s_cmp_eq_u32 s6, 3
	s_cbranch_scc1 .Lsc_loader_c
	s_branch .Lsc_loader_a
.Lsc_consumer:
	s_waitcnt vmcnt(0)
	v_add_u32_e32 v171, s22, v2
	s_mov_b32 s10, 0
	s_mov_b32 s11, 0
	s_mov_b32 s8, 1
.Lc_poll_p:
	ds_read_b96 v[244:246], v173
	s_waitcnt lgkmcnt(0)
	v_min3_u32 v244, v244, v245, v246
	s_nop 0
	v_readfirstlane_b32 s6, v244
	s_nop 1
	s_cmp_ge_u32 s6, s8
	s_cbranch_scc1 .Lc_rdy_p
	s_sleep 1
	s_branch .Lc_poll_p
.Lc_rdy_p:
	v_mov_b32_e32 v247, v171
	ds_read_b128 v[36:39], v247
	ds_read_b128 v[40:43], v247 offset:1024
	ds_read_b128 v[44:47], v247 offset:2048
	ds_read_b128 v[48:51], v247 offset:3072
	ds_read_b128 v[52:55], v247 offset:4096
	ds_read_b128 v[56:59], v247 offset:5120
	ds_read_b128 v[60:63], v247 offset:6144
	ds_read_b128 v[64:67], v247 offset:7168
	ds_read_b128 v[68:71], v247 offset:8192
	ds_read_b128 v[72:75], v247 offset:9216
	ds_read_b128 v[76:79], v247 offset:10240
	ds_read_b128 v[80:83], v247 offset:11264
	s_waitcnt lgkmcnt(0)
	v_mov_b32_e32 v248, 1
	ds_write_b32 v173, v248 offset:12
.Lc_loop:
	s_add_i32 s8, s10, 2
	s_add_i32 s9, s10, 1
	s_cmp_ge_u32 s9, s30
	s_cbranch_scc1 .Lc_nopf_0

; DI void phase_scan(KArgs args, LAS unsigned char* L, const Ctx& c) {
;     ...
;         SCAN_DMA(); SCAN_DMA(); SCAN_DMA(); SCAN_DMA(); SCAN_DMA();
;         asm volatile("s_waitcnt vmcnt(48)" ::: "memory"); SCAN_LOAD(0);
;         asm volatile("s_waitcnt vmcnt(36)" ::: "memory"); SCAN_LOAD(1);
;         for (int step = 0; step < nch; step += 2) {
;             SCAN_STEP(0, step);     asm volatile("s_waitcnt vmcnt(24)" ::: "memory"); SCAN_LOAD(0); SCAN_DMA();
;             SCAN_STEP(1, step + 1); asm volatile("s_waitcnt vmcnt(24)" ::: "memory"); SCAN_LOAD(1); SCAN_DMA();
.Lc_rdy_l0:
	s_add_i32 s11, s11, 1
	s_cmp_eq_u32 s11, 5
	s_cselect_b32 s11, 0, s11
	s_mul_i32 s6, s11, 0x3000
	v_add_u32_e32 v247, s6, v171
	ds_read_b128 v[84:87], v247
	ds_read_b128 v[88:91], v247 offset:1024
	ds_read_b128 v[92:95], v247 offset:2048
	ds_read_b128 v[96:99], v247 offset:3072
	ds_read_b128 v[100:103], v247 offset:4096
	ds_read_b128 v[104:107], v247 offset:5120
	ds_read_b128 v[108:111], v247 offset:6144
	ds_read_b128 v[112:115], v247 offset:7168
	ds_read_b128 v[116:119], v247 offset:8192
	ds_read_b128 v[120:123], v247 offset:9216
	ds_read_b128 v[124:127], v247 offset:10240
	ds_read_b128 v[128:131], v247 offset:11264
.Lc_nopf_0:
	s_lshr_b32 s6, s10, 6
	s_cmp_lt_u32 s10, 64
	s_cselect_b64 vcc, -1, 0
	s_cmp_eq_u32 s6, 1
	s_cselect_b64 s[4:5], -1, 0
	s_cmp_eq_u32 s6, 2
	s_cselect_b64 s[6:7], -1, 0
	v_cndmask_b32_e64 v172, v170, v169, s[6:7]
	v_cndmask_b32_e64 v172, v172, v168, s[4:5]
	v_cndmask_b32_e32 v172, v172, v1, vcc
	v_cvt_pk_bf16_f32 v132, v4, v5
	v_cvt_pk_bf16_f32 v133, v6, v7
	v_cvt_pk_bf16_f32 v134, v8, v9
	v_cvt_pk_bf16_f32 v135, v10, v11
	v_cvt_pk_bf16_f32 v136, v12, v13
	v_cvt_pk_bf16_f32 v137, v14, v15
	v_cvt_pk_bf16_f32 v138, v16, v17
	v_cvt_pk_bf16_f32 v139, v18, v19
	v_cvt_pk_bf16_f32 v140, v20, v21
	v_cvt_pk_bf16_f32 v141, v22, v23
	v_cvt_pk_bf16_f32 v142, v24, v25
	v_cvt_pk_bf16_f32 v143, v26, v27
	v_cvt_pk_bf16_f32 v144, v28, v29
	v_cvt_pk_bf16_f32 v145, v30, v31
	v_cvt_pk_bf16_f32 v146, v32, v33
	v_cvt_pk_bf16_f32 v147, v34, v35
	v_readlane_b32 s4, v172, s10
	s_waitcnt vmcnt(12)
	global_store_dwordx4 v[166:167], v[132:135], off offset:-2048
	global_store_dwordx4 v[166:167], v[136:139], off offset:-1024
	global_store_dwordx4 v[166:167], v[140:143], off
	global_store_dwordx4 v[166:167], v[144:147], off offset:1024
	v_lshlrev_b32_e32 v174, 16, v68
	v_and_b32_e32 v175, 0xffff0000, v68
	v_pk_fma_f32 v[4:5], v[4:5], s[4:5], v[174:175] op_sel_hi:[1,0,1]
	v_lshlrev_b32_e32 v174, 16, v69
	v_and_b32_e32 v175, 0xffff0000, v69
	v_pk_fma_f32 v[6:7], v[6:7], s[4:5], v[174:175] op_sel_hi:[1,0,1]
	v_lshlrev_b32_e32 v174, 16, v70
	v_and_b32_e32 v175, 0xffff0000, v70
	v_pk_fma_f32 v[8:9], v[8:9], s[4:5], v[174:175] op_sel_hi:[1,0,1]
	v_lshlrev_b32_e32 v174, 16, v71
	v_and_b32_e32 v175, 0xffff0000, v71
	v_pk_fma_f32 v[10:11], v[10:11], s[4:5], v[174:175] op_sel_hi:[1,0,1]
	v_lshlrev_b32_e32 v174, 16, v72
	v_and_b32_e32 v175, 0xffff0000, v72
	v_pk_fma_f32 v[12:13], v[12:13], s[4:5], v[174:175] op_sel_hi:[1,0,1]
	v_lshlrev_b32_e32 v174, 16, v73
	v_and_b32_e32 v175, 0xffff0000, v73
	v_pk_fma_f32 v[14:15], v[14:15], s[4:5], v[174:175] op_sel_hi:[1,0,1]
	v_lshlrev_b32_e32 v174, 16, v74
	v_and_b32_e32 v175, 0xffff0000, v74
	v_pk_fma_f32 v[16:17], v[16:17], s[4:5], v[174:175] op_sel_hi:[1,0,1]
	v_lshlrev_b32_e32 v174, 16, v75
	v_and_b32_e32 v175, 0xffff0000, v75
	v_pk_fma_f32 v[18:19], v[18:19], s[4:5], v[174:175] op_sel_hi:[1,0,1]
	v_lshlrev_b32_e32 v174, 16, v76
	v_and_b32_e32 v175, 0xffff0000, v76
	v_pk_fma_f32 v[20:21], v[20:21], s[4:5], v[174:175] op_sel_hi:[1,0,1]
	v_lshlrev_b32_e32 v174, 16, v77
	v_and_b32_e32 v175, 0xffff0000, v77
	v_pk_fma_f32 v[22:23], v[22:23], s[4:5], v[174:175] op_sel_hi:[1,0,1]
	v_lshlrev_b32_e32 v174, 16, v78
	v_and_b32_e32 v175, 0xffff0000, v78
	v_pk_fma_f32 v[24:25], v[24:25], s[4:5], v[174:175] op_sel_hi:[1,0,1]
	v_lshlrev_b32_e32 v174, 16, v79
	v_and_b32_e32 v175, 0xffff0000, v79
	v_pk_fma_f32 v[26:27], v[26:27], s[4:5], v[174:175] op_sel_hi:[1,0,1]
	v_lshlrev_b32_e32 v174, 16, v80
	v_and_b32_e32 v175, 0xffff0000, v80
	v_pk_fma_f32 v[28:29], v[28:29], s[4:5], v[174:175] op_sel_hi:[1,0,1]
	v_lshlrev_b32_e32 v174, 16, v81
	v_and_b32_e32 v175, 0xffff0000, v81
	v_pk_fma_f32 v[30:31], v[30:31], s[4:5], v[174:175] op_sel_hi:[1,0,1]
	v_lshlrev_b32_e32 v174, 16, v82
	v_and_b32_e32 v175, 0xffff0000, v82
	v_pk_fma_f32 v[32:33], v[32:33], s[4:5], v[174:175] op_sel_hi:[1,0,1]
	v_lshlrev_b32_e32 v174, 16, v83
	v_and_b32_e32 v175, 0xffff0000, v83
	v_pk_fma_f32 v[34:35], v[34:35], s[4:5], v[174:175] op_sel_hi:[1,0,1]
	s_nop 1
	v_mfma_f32_32x32x16_bf16 v[4:19], v[36:39], v[132:135], v[4:19]
	v_mfma_f32_32x32x16_bf16 v[20:35], v[52:55], v[132:135], v[20:35]
	v_mfma_f32_32x32x16_bf16 v[4:19], v[40:43], v[136:139], v[4:19]
	v_mfma_f32_32x32x16_bf16 v[20:35], v[56:59], v[136:139], v[20:35]
	v_mfma_f32_32x32x16_bf16 v[4:19], v[44:47], v[140:143], v[4:19]
	v_mfma_f32_32x32x16_bf16 v[20:35], v[60:63], v[140:143], v[20:35]
	v_mfma_f32_32x32x16_bf16 v[4:19], v[48:51], v[144:147], v[4:19]
	v_mfma_f32_32x32x16_bf16 v[20:35], v[64:67], v[144:147], v[20:35]
	v_lshl_add_u64 v[166:167], v[166:167], 0, s[0:1]
	s_waitcnt lgkmcnt(0)
	v_mov_b32_e32 v248, s8
	ds_write_b32 v173, v248 offset:12
	s_add_i32 s10, s10, 1
	s_cmp_ge_u32 s10, s30
	s_cbranch_scc1 .Lc_exit
	s_add_i32 s8, s10, 2
	s_add_i32 s9, s10, 1
	s_cmp_ge_u32 s9, s30
	s_cbranch_scc1 .Lc_nopf_1

; DI void phase_scan(KArgs args, LAS unsigned char* L, const Ctx& c) {
;     ...
;         SCAN_DMA(); SCAN_DMA(); SCAN_DMA(); SCAN_DMA(); SCAN_DMA();
;         asm volatile("s_waitcnt vmcnt(48)" ::: "memory"); SCAN_LOAD(0);
;         asm volatile("s_waitcnt vmcnt(36)" ::: "memory"); SCAN_LOAD(1);
;         for (int step = 0; step < nch; step += 2) {
;             SCAN_STEP(0, step);     asm volatile("s_waitcnt vmcnt(24)" ::: "memory"); SCAN_LOAD(0); SCAN_DMA();
;             SCAN_STEP(1, step + 1); asm volatile("s_waitcnt vmcnt(24)" ::: "memory"); SCAN_LOAD(1); SCAN_DMA();
;         }
;         asm volatile("s_waitcnt vmcnt(0)" ::: "memory");
.Lc_rdy_l1:
	s_add_i32 s11, s11, 1
	s_cmp_eq_u32 s11, 5
	s_cselect_b32 s11, 0, s11
	s_mul_i32 s6, s11, 0x3000
	v_add_u32_e32 v247, s6, v171
	ds_read_b128 v[36:39], v247
	ds_read_b128 v[40:43], v247 offset:1024
	ds_read_b128 v[44:47], v247 offset:2048
	ds_read_b128 v[48:51], v247 offset:3072
	ds_read_b128 v[52:55], v247 offset:4096
	ds_read_b128 v[56:59], v247 offset:5120
	ds_read_b128 v[60:63], v247 offset:6144
	ds_read_b128 v[64:67], v247 offset:7168
	ds_read_b128 v[68:71], v247 offset:8192
	ds_read_b128 v[72:75], v247 offset:9216
	ds_read_b128 v[76:79], v247 offset:10240
	ds_read_b128 v[80:83], v247 offset:11264
.Lc_nopf_1:
	s_lshr_b32 s6, s10, 6
	s_cmp_lt_u32 s10, 64
	s_cselect_b64 vcc, -1, 0
	s_cmp_eq_u32 s6, 1
	s_cselect_b64 s[4:5], -1, 0
	s_cmp_eq_u32 s6, 2
	s_cselect_b64 s[6:7], -1, 0
	v_cndmask_b32_e64 v172, v170, v169, s[6:7]
	v_cndmask_b32_e64 v172, v172, v168, s[4:5]
	v_cndmask_b32_e32 v172, v172, v1, vcc
	v_cvt_pk_bf16_f32 v132, v4, v5
	v_cvt_pk_bf16_f32 v133, v6, v7
	v_cvt_pk_bf16_f32 v134, v8, v9
	v_cvt_pk_bf16_f32 v135, v10, v11
	v_cvt_pk_bf16_f32 v136, v12, v13
	v_cvt_pk_bf16_f32 v137, v14, v15
	v_cvt_pk_bf16_f32 v138, v16, v17
	v_cvt_pk_bf16_f32 v139, v18, v19
	v_cvt_pk_bf16_f32 v140, v20, v21
	v_cvt_pk_bf16_f32 v141, v22, v23
	v_cvt_pk_bf16_f32 v142, v24, v25
	v_cvt_pk_bf16_f32 v143, v26, v27
	v_cvt_pk_bf16_f32 v144, v28, v29
	v_cvt_pk_bf16_f32 v145, v30, v31
	v_cvt_pk_bf16_f32 v146, v32, v33
	v_cvt_pk_bf16_f32 v147, v34, v35
	v_readlane_b32 s4, v172, s10
	s_waitcnt vmcnt(12)
	global_store_dwordx4 v[166:167], v[132:135], off offset:-2048
	global_store_dwordx4 v[166:167], v[136:139], off offset:-1024
	global_store_dwordx4 v[166:167], v[140:143], off
	global_store_dwordx4 v[166:167], v[144:147], off offset:1024
	v_lshlrev_b32_e32 v174, 16, v116
	v_and_b32_e32 v175, 0xffff0000, v116
	v_pk_fma_f32 v[4:5], v[4:5], s[4:5], v[174:175] op_sel_hi:[1,0,1]
	v_lshlrev_b32_e32 v174, 16, v117
	v_and_b32_e32 v175, 0xffff0000, v117
	v_pk_fma_f32 v[6:7], v[6:7], s[4:5], v[174:175] op_sel_hi:[1,0,1]
	v_lshlrev_b32_e32 v174, 16, v118
	v_and_b32_e32 v175, 0xffff0000, v118
	v_pk_fma_f32 v[8:9], v[8:9], s[4:5], v[174:175] op_sel_hi:[1,0,1]
	v_lshlrev_b32_e32 v174, 16, v119
	v_and_b32_e32 v175, 0xffff0000, v119
	v_pk_fma_f32 v[10:11], v[10:11], s[4:5], v[174:175] op_sel_hi:[1,0,1]
	v_lshlrev_b32_e32 v174, 16, v120
	v_and_b32_e32 v175, 0xffff0000, v120
	v_pk_fma_f32 v[12:13], v[12:13], s[4:5], v[174:175] op_sel_hi:[1,0,1]
	v_lshlrev_b32_e32 v174, 16, v121
	v_and_b32_e32 v175, 0xffff0000, v121
	v_pk_fma_f32 v[14:15], v[14:15], s[4:5], v[174:175] op_sel_hi:[1,0,1]
	v_lshlrev_b32_e32 v174, 16, v122
	v_and_b32_e32 v175, 0xffff0000, v122
	v_pk_fma_f32 v[16:17], v[16:17], s[4:5], v[174:175] op_sel_hi:[1,0,1]
	v_lshlrev_b32_e32 v174, 16, v123
	v_and_b32_e32 v175, 0xffff0000, v123
	v_pk_fma_f32 v[18:19], v[18:19], s[4:5], v[174:175] op_sel_hi:[1,0,1]
	v_lshlrev_b32_e32 v174, 16, v124
	v_and_b32_e32 v175, 0xffff0000, v124
	v_pk_fma_f32 v[20:21], v[20:21], s[4:5], v[174:175] op_sel_hi:[1,0,1]
	v_lshlrev_b32_e32 v174, 16, v125
	v_and_b32_e32 v175, 0xffff0000, v125
	v_pk_fma_f32 v[22:23], v[22:23], s[4:5], v[174:175] op_sel_hi:[1,0,1]
	v_lshlrev_b32_e32 v174, 16, v126
	v_and_b32_e32 v175, 0xffff0000, v126
	v_pk_fma_f32 v[24:25], v[24:25], s[4:5], v[174:175] op_sel_hi:[1,0,1]
	v_lshlrev_b32_e32 v174, 16, v127
	v_and_b32_e32 v175, 0xffff0000, v127
	v_pk_fma_f32 v[26:27], v[26:27], s[4:5], v[174:175] op_sel_hi:[1,0,1]
	v_lshlrev_b32_e32 v174, 16, v128
	v_and_b32_e32 v175, 0xffff0000, v128
	v_pk_fma_f32 v[28:29], v[28:29], s[4:5], v[174:175] op_sel_hi:[1,0,1]
	v_lshlrev_b32_e32 v174, 16, v129
	v_and_b32_e32 v175, 0xffff0000, v129
	v_pk_fma_f32 v[30:31], v[30:31], s[4:5], v[174:175] op_sel_hi:[1,0,1]
	v_lshlrev_b32_e32 v174, 16, v130
	v_and_b32_e32 v175, 0xffff0000, v130
	v_pk_fma_f32 v[32:33], v[32:33], s[4:5], v[174:175] op_sel_hi:[1,0,1]
	v_lshlrev_b32_e32 v174, 16, v131
	v_and_b32_e32 v175, 0xffff0000, v131
	v_pk_fma_f32 v[34:35], v[34:35], s[4:5], v[174:175] op_sel_hi:[1,0,1]
	s_nop 1
	v_mfma_f32_32x32x16_bf16 v[4:19], v[84:87], v[132:135], v[4:19]
	v_mfma_f32_32x32x16_bf16 v[20:35], v[100:103], v[132:135], v[20:35]
	v_mfma_f32_32x32x16_bf16 v[4:19], v[88:91], v[136:139], v[4:19]
	v_mfma_f32_32x32x16_bf16 v[20:35], v[104:107], v[136:139], v[20:35]
	v_mfma_f32_32x32x16_bf16 v[4:19], v[92:95], v[140:143], v[4:19]
	v_mfma_f32_32x32x16_bf16 v[20:35], v[108:111], v[140:143], v[20:35]
	v_mfma_f32_32x32x16_bf16 v[4:19], v[96:99], v[144:147], v[4:19]
	v_mfma_f32_32x32x16_bf16 v[20:35], v[112:115], v[144:147], v[20:35]
	v_lshl_add_u64 v[166:167], v[166:167], 0, s[0:1]
	s_waitcnt lgkmcnt(0)
	v_mov_b32_e32 v248, s8
	ds_write_b32 v173, v248 offset:12
	s_add_i32 s10, s10, 1
	s_cmp_ge_u32 s10, s30
	s_cbranch_scc1 .Lc_exit
	s_branch .Lc_loop
.Lc_exit:
	s_waitcnt vmcnt(0) lgkmcnt(0)
	v_mov_b32_e32 v248, 0
	ds_write_b32 v173, v248
	ds_write_b32 v173, v248 offset:4
	ds_write_b32 v173, v248 offset:8
	ds_write_b32 v173, v248 offset:12
	s_waitcnt lgkmcnt(0)
	s_setprio 0
	s_branch .LBB0_651
.Lsc_loader_a:
	s_mov_b32 s10, 0
	s_mov_b32 s11, 0
	s_add_u32 s12, s2, s20
	s_addc_u32 s13, s3, 0
.Lla_loop:
.Lla_poll:
	ds_read_b32 v244, v173 offset:12
	s_waitcnt lgkmcnt(0)
	v_readfirstlane_b32 s6, v244
	s_nop 1
	s_sub_i32 s7, s10, s6
	s_cmp_lt_i32 s7, 5
	s_cbranch_scc1 .Lla_go
	s_sleep 1
	s_branch .Lla_poll
.Lla_go:
	s_mul_i32 s7, s11, 0x3000
	s_add_i32 s7, s7, s22
	s_add_i32 s7, s7, s20
	s_mov_b32 m0, s7
	s_nop 0
	global_load_lds_dwordx4 v2, s[12:13]
	global_load_lds_dwordx4 v2, s[12:13] offset:1024
	global_load_lds_dwordx4 v2, s[12:13] offset:2048
	global_load_lds_dwordx4 v2, s[12:13] offset:3072
	s_add_i32 s10, s10, 1
	s_add_i32 s11, s11, 1
	s_cmp_eq_u32 s11, 5
	s_cselect_b32 s11, 0, s11
	s_cmp_le_u32 s10, s31
	s_cselect_b32 s6, s0, 0
	s_cselect_b32 s7, s1, 0
	s_add_u32 s12, s12, s6
	s_addc_u32 s13, s13, s7
	s_waitcnt vmcnt(12)
	s_sub_i32 s6, s10, 3
	s_max_i32 s6, s6, 0
	v_mov_b32_e32 v245, s6
	ds_write_b32 v246, v245
	s_cmp_lt_u32 s10, s30
	s_cbranch_scc1 .Lla_loop
	s_waitcnt vmcnt(0)
	v_mov_b32_e32 v245, s10
	ds_write_b32 v246, v245
	s_waitcnt lgkmcnt(0)
	s_setprio 0
	s_branch .LBB0_651

.Llc_go:
	s_mul_i32 s7, s11, 0x3000
	s_add_i32 s7, s7, s22
	s_add_i32 s7, s7, s20
	s_mov_b32 m0, s7
	s_nop 0
	global_load_lds_dwordx4 v162, s[12:13]
	s_add_i32 m0, s7, 0x3f0
	s_nop 0
	global_load_lds_dwordx4 v162, s[12:13] offset:16
	s_add_i32 m0, s7, 0x800
	s_nop 0
	global_load_lds_dwordx4 v164, s[12:13]
	s_add_i32 m0, s7, 0xbf0
	s_nop 0
	global_load_lds_dwordx4 v164, s[12:13] offset:16
	s_add_i32 s10, s10, 1
	s_add_i32 s11, s11, 1
	s_cmp_eq_u32 s11, 5
	s_cselect_b32 s11, 0, s11
	s_cmp_le_u32 s10, s31
	s_cselect_b32 s6, s0, 0
	s_cselect_b32 s7, s1, 0
	s_add_u32 s12, s12, s6
	s_addc_u32 s13, s13, s7
	s_waitcnt vmcnt(12)
	s_sub_i32 s6, s10, 3
	s_max_i32 s6, s6, 0
	v_mov_b32_e32 v245, s6
	ds_write_b32 v246, v245
	s_cmp_lt_u32 s10, s30
	s_cbranch_scc1 .Llc_loop
	s_waitcnt vmcnt(0)
	v_mov_b32_e32 v245, s10
	ds_write_b32 v246, v245
	s_waitcnt lgkmcnt(0)
	s_setprio 0
	s_branch .LBB0_651
